# diff attention: no static priority raise for waves 4-7
# speedup vs baseline: 1.0016x; 1.0016x over previous
; template <int MODE, int ORD> ...
;     ...
;   int tid_ = threadIdx.x; asm volatile("" : "+v"(tid_));
;   const int tid = tid_, wid = __builtin_amdgcn_readfirstlane(tid >> 6), lane = tid & 63; int r32 = lane & 31, hi = lane >> 5;
;   const int wq = MODE == 0 ? (wid & 3) : wid, cst = MODE == 0 ? (wid >> 2) : 0;
;   char* V_lds = lds + OFF_V; char* K_lds = lds + OFF_K;
;   float* wsf = (float*)(lds + OFF_WS) + wid * 64; float* li_l = wsf; float* al_l = wsf + 32;
;   float* tab = (float*)(lds + OFF_TAB);
;   __syncthreads();
;   if (wid >= 4) __builtin_amdgcn_s_setprio(1);
.LBB0_153:
	v_mov_b32_e32 v40, v244
	s_nop 0
	v_readfirstlane_b32 s63, v40
	s_ashr_i32 s62, s63, 6
	s_cmp_lt_i32 s62, 4
	s_barrier
	s_cbranch_scc1 .LBB0_155
	s_setprio 0
